# nosleep: s_sleep removed from the 10 seam/exchange poll loops (tighter polling)
# speedup vs baseline: 1.0089x; 1.0047x over previous
.Llb_spin_s1:
	global_load_dword v2, v3, s[4:5] sc1
	s_waitcnt vmcnt(0)
	v_cmp_gt_u32_e32 vcc, 1, v2
	s_cbranch_vccz .Llb_acq_s1
	s_add_i32 s99, s99, 1
	s_cmp_lt_u32 s99, 0x40000
	s_cbranch_scc1 .Llb_spin_s1

.Llb_spin_s2:
	global_load_dword v2, v3, s[4:5] sc1
	s_waitcnt vmcnt(0)
	v_cmp_gt_u32_e32 vcc, 2, v2
	s_cbranch_vccz .Llb_acq_s2
	s_add_i32 s99, s99, 1
	s_cmp_lt_u32 s99, 0x40000
	s_cbranch_scc1 .Llb_spin_s2

.Llb_spin_s3:
	global_load_dword v2, v3, s[4:5] sc1
	s_waitcnt vmcnt(0)
	v_cmp_gt_u32_e32 vcc, 3, v2
	s_cbranch_vccz .Llb_acq_s3
	s_add_i32 s99, s99, 1
	s_cmp_lt_u32 s99, 0x40000
	s_cbranch_scc1 .Llb_spin_s3

.Llb_g3_s3:
	global_load_dword v4, v5, s[10:11] sc1
	s_waitcnt vmcnt(0)
	v_cmp_le_u32_e32 vcc, s25, v4
	s_cbranch_vccnz .Llb_g3d_s3
	s_add_i32 s99, s99, 1
	s_cmp_lt_u32 s99, 0x40000
	s_cbranch_scc1 .Llb_g3_s3

.Llb_spin_s4:
	global_load_dword v2, v3, s[4:5] sc1
	s_waitcnt vmcnt(0)
	v_cmp_gt_u32_e32 vcc, 4, v2
	s_cbranch_vccz .Llb_acq_s4
	s_add_i32 s99, s99, 1
	s_cmp_lt_u32 s99, 0x40000
	s_cbranch_scc1 .Llb_spin_s4

.Llb_spin_s5:
	global_load_dword v2, v3, s[4:5] sc1
	s_waitcnt vmcnt(0)
	v_cmp_gt_u32_e32 vcc, 5, v2
	s_cbranch_vccz .Llb_acq_s5
	s_add_i32 s99, s99, 1
	s_cmp_lt_u32 s99, 0x40000
	s_cbranch_scc1 .Llb_spin_s5

.Lxs7_spin:
	global_load_dword v9, v8, s[0:1] sc1
	s_waitcnt vmcnt(0)
	v_cmp_gt_u32_e32 vcc, 1, v9
	s_cbranch_vccz .LBB0_595
	s_add_i32 s40, s40, -1
	s_cmp_eq_u32 s40, 0
	s_cbranch_scc1 .LBB0_595
	s_branch .Lxs7_spin

.Llb_spin_s7:
	global_load_dword v2, v3, s[4:5] sc1
	s_waitcnt vmcnt(0)
	v_cmp_gt_u32_e32 vcc, 6, v2
	s_cbranch_vccz .Llb_acq_s7
	s_add_i32 s99, s99, 1
	s_cmp_lt_u32 s99, 0x40000
	s_cbranch_scc1 .Llb_spin_s7

.Llb_spin_s8:
	global_load_dword v2, v3, s[4:5] sc1
	s_waitcnt vmcnt(0)
	v_cmp_gt_u32_e32 vcc, 7, v2
	s_cbranch_vccz .Llb_acq_s8
	s_add_i32 s99, s99, 1
	s_cmp_lt_u32 s99, 0x40000
	s_cbranch_scc1 .Llb_spin_s8

.Lxs9_spin:
	global_load_dword v3, v2, s[0:1] sc1
	s_waitcnt vmcnt(0)
	v_cmp_gt_u32_e32 vcc, 1, v3
	s_cbranch_vccz .LBB0_748
	s_add_i32 s14, s14, -1
	s_cmp_eq_u32 s14, 0
	s_cbranch_scc1 .LBB0_748
	s_branch .Lxs9_spin
